# grid barrier: non-leader blocks poll the top-level generation word directly (one hop less per barrier)
# speedup vs baseline: 1.0037x; 1.0037x over previous
; __device__ __forceinline__ unsigned xb_ld(unsigned* p)              { return __hip_atomic_load(p, __ATOMIC_RELAXED, __HIP_MEMORY_SCOPE_AGENT); }
; __device__ __forceinline__ unsigned xb_add(unsigned* p, unsigned v) { return __hip_atomic_fetch_add(p, v, __ATOMIC_RELAXED, __HIP_MEMORY_SCOPE_AGENT); }
; #define XB_SPIN(cond, bar) do { unsigned _sp = 0; while (cond) { __builtin_amdgcn_s_sleep(1); \
;     if ((++_sp & 255u) == 0u) { if (xb_ld(&(bar)[XB_TMO])) break; if (_sp > XB_SPIN_CAP) { atomicAdd(&(bar)[XB_TMO], 1u); break; } } } } while (0)
; __device__ __forceinline__ void xcd_barrier(unsigned* bar, volatile LAS unsigned* st, bool is_t0, unsigned G) {
;     ...
;         const unsigned old = xb_add(&bar[XB_XSUB(x)], 1u);
;         const unsigned gen = old / nloc;
;         if (old + 1u == (gen + 1u) * nloc) {
;             __builtin_amdgcn_fence(__ATOMIC_RELEASE, "agent");
;             asm volatile("s_waitcnt vmcnt(0)" ::: "memory");
;             const unsigned og = xb_add(&bar[XB_TOP], 1u);
;             const unsigned tg = og / nx;
;             if (og + 1u == (tg + 1u) * nx) xb_add(&bar[XB_TOPGEN], 1u);
;             else XB_SPIN(xb_ld(&bar[XB_TOPGEN]) == tg, bar);
;             __builtin_amdgcn_fence(__ATOMIC_ACQUIRE, "agent");
;             xb_add(&bar[XB_XGEN(x)], 1u);
;             asm volatile("s_waitcnt vmcnt(0)" ::: "memory");
;         } else {
;             XB_SPIN(xb_ld(&bar[XB_XGEN(x)]) == gen, bar);
;             __builtin_amdgcn_fence(__ATOMIC_ACQUIRE, "agent");
;             asm volatile("s_waitcnt vmcnt(0)" ::: "memory");
;         }
.LBB0_660:
	s_or_b64 exec, exec, s[12:13]
	v_cvt_f32_u32_e32 v4, v2
	s_waitcnt vmcnt(0)
	v_readfirstlane_b32 s0, v3
	v_sub_u32_e32 v3, 0, v2
	v_rcp_iflag_f32_e32 v4, v4
	v_add_u32_e32 v5, s0, v1
	v_mul_f32_e32 v4, 0x4f7ffffe, v4
	v_cvt_u32_f32_e32 v4, v4
	v_mul_lo_u32 v1, v3, v4
	v_mul_hi_u32 v1, v4, v1
	v_add_u32_e32 v1, v4, v1
	v_mul_hi_u32 v1, v5, v1
	v_mul_lo_u32 v3, v1, v2
	v_sub_u32_e32 v3, v5, v3
	v_add_u32_e32 v4, 1, v1
	v_cmp_ge_u32_e32 vcc, v3, v2
	s_nop 1
	v_cndmask_b32_e32 v1, v1, v4, vcc
	v_sub_u32_e32 v4, v3, v2
	v_cndmask_b32_e32 v3, v3, v4, vcc
	v_add_u32_e32 v4, 1, v1
	v_cmp_ge_u32_e32 vcc, v3, v2
	v_add_u32_e32 v3, 1, v5
	s_nop 0
	v_cndmask_b32_e32 v1, v1, v4, vcc
	v_mul_lo_u32 v4, v2, v1
	v_add_u32_e32 v2, v4, v2
	v_cmp_ne_u32_e32 vcc, v3, v2
	s_and_saveexec_b64 s[10:11], vcc
	s_xor_b64 s[10:11], exec, s[10:11]
	s_cbranch_execz .LBB0_674
	s_waitcnt lgkmcnt(0)
	v_readlane_b32 s62, v254, 6
	v_readlane_b32 s63, v254, 7
	s_nop 4
	global_load_dword v0, v177, s[62:63] sc1
	s_waitcnt vmcnt(0)
	v_cmp_eq_u32_e32 vcc, v0, v1
	s_and_saveexec_b64 s[12:13], vcc
	s_cbranch_execz .LBB0_673
	s_mov_b32 s0, 1
	s_mov_b64 s[68:69], 0
	s_branch .LBB0_664
